# in-proj/up-proj phase start: redundant store-ack wait + workgroup barrier after row_scales removed (the GEMM prologue's counted wait + barrier already orders the rstd stores)
# baseline (speedup 1.0000x reference)
; template <class Epi, class Sched, bool ALIGN_EPI = false, bool SP2 = false>
; __device__ __forceinline__ void gemm_phase(PG8_LAS unsigned char* lds, const Gemm g, const Sched& S, const Epi& E, int tid_in) {
;     int tid_ = tid_in; asm volatile("" : "+v"(tid_));
;     const int tid = tid_, wid = __builtin_amdgcn_readfirstlane(tid >> 6), lane = tid & 63, wr = wid >> 2, wc = wid & 3, fr = lane & 15, fq = lane >> 4;
; template <class Sched> DI void row_scales(const Sched& S, const float* slots2, float* rstdx, int tid) {
;     ...
;     asm volatile("s_waitcnt vmcnt(0)" ::: "memory");
;     __syncthreads();
.LBB0_231:
	s_or_b64 exec, exec, s[14:15]
	v_mbcnt_lo_u32_b32 v0, -1, 0
	v_mbcnt_hi_u32_b32 v0, -1, v0
	s_cmpk_lt_i32 s4, 0xb00
	v_add_u32_e32 v8, s82, v0
	s_cselect_b64 s[12:13], -1, 0
	s_cmpk_gt_i32 s4, 0xaff
	v_readfirstlane_b32 s18, v8
	s_cbranch_scc1 .LBB0_233
	s_lshr_b32 s8, s5, 29
	s_add_i32 s8, s4, s8
	s_ashr_i32 s9, s8, 3
	s_and_b32 s8, s8, -8
	s_sub_i32 s8, s4, s8
	s_cmp_lt_i32 s8, 0
	s_movk_i32 s14, 0x160
	s_cselect_b32 s14, 0x161, s14
	s_mul_i32 s8, s8, s14
	s_add_i32 s8, s8, s9
	s_mul_hi_i32 s9, s8, 0x2e8ba2e9
	s_lshr_b32 s14, s9, 31
	s_ashr_i32 s9, s9, 5
	s_add_i32 s9, s9, s14
	s_lshl_b32 s14, s9, 3
	s_mulk_i32 s9, 0xb0
	s_sub_i32 s8, s8, s9
	s_bfe_u32 s9, s8, 0x3001c
	s_add_i32 s9, s8, s9
	s_sext_i32_i16 s15, s9
	s_and_b32 s9, s9, 0xfff8
	s_sub_i32 s8, s8, s9
	s_sext_i32_i16 s8, s8
	s_add_i32 s24, s14, s8
	s_ashr_i32 s22, s15, 3

; template <class Epi, class Sched, bool ALIGN_EPI = false, bool SP2 = false>
; __device__ __forceinline__ void gemm_phase(PG8_LAS unsigned char* lds, const Gemm g, const Sched& S, const Epi& E, int tid_in) {
;     int tid_ = tid_in; asm volatile("" : "+v"(tid_));
;     const int tid = tid_, wid = __builtin_amdgcn_readfirstlane(tid >> 6), lane = tid & 63, wr = wid >> 2, wc = wid & 3, fr = lane & 15, fq = lane >> 4;
; template <class Sched> DI void row_scales(const Sched& S, const float* slots2, float* rstdx, int tid) {
;     ...
;     asm volatile("s_waitcnt vmcnt(0)" ::: "memory");
;     __syncthreads();
.LBB0_737:
	s_or_b64 exec, exec, s[12:13]
	v_mbcnt_lo_u32_b32 v0, -1, 0
	v_mbcnt_hi_u32_b32 v0, -1, v0
	s_cmpk_gt_i32 s4, 0x3ff
	v_add_u32_e32 v8, s82, v0
	s_nop 0
	v_readfirstlane_b32 s15, v8
	s_cbranch_scc1 .LBB0_761
	s_lshr_b32 s6, s5, 29
	s_add_i32 s6, s4, s6
	s_and_b32 s7, s6, -8
	s_sub_i32 s7, s4, s7
	s_cmp_gt_i32 s7, -1
	s_mov_b64 s[10:11], -1
	s_cbranch_scc0 .LBB0_740
	s_lshl_b32 s12, s7, 7
	s_mov_b64 s[10:11], 0
